# residual epilogue (P4/P7): residual loads also widened to 16 dwordx4 (load with store-side lane offsets, permlane16_swap back to the compute layout)
# baseline (speedup 1.0000x reference)
; __device__ __forceinline__ unsigned pk2(float lo, float hi) { const bf16x2_t v = __builtin_convertvector((f32x2_t){lo, hi}, bf16x2_t); return __builtin_bit_cast(unsigned, v); }
; __device__ __forceinline__ float bf_lo(unsigned w) { return __uint_as_float(w << 16); }
; __device__ __forceinline__ float bf_hi(unsigned w) { return __uint_as_float(w & 0xffff0000u); }
;     __device__ __forceinline__ void row(int ai, int m, const f32x4 (&v)[2][2], const Unit& u, int wr, int wc, int fr, int fq) const {
;         const int row0 = u.pm * BM + wr * 64 + fr, col0 = u.pn * BM + wc * 32 + 4 * fq;
;         const size_t off = (size_t)(row0 + ai * HALF + m * 16) * DM + col0;
; #pragma unroll
;         for (int bj = 0; bj < 2; ++bj)
; #pragma unroll
;             for (int n = 0; n < 2; ++n) { const u32x2 rb = *(const u32x2*)(res + off + bj * HALF + n * 16);
;                 const f32x4 r = (f32x4){bf_lo(rb.x), bf_hi(rb.x), bf_lo(rb.y), bf_hi(rb.y)}; const f32x4 o = v[bj][n] + ALPHA * r;
;                 u32x2 w; w.x = pk2(o[0], o[1]); w.y = pk2(o[2], o[3]); *(u32x2*)(C + off + bj * HALF + n * 16) = w; }
;     }
.LBB0_912:
	v_lshl_add_u32 v142, s30, 8, v144
	v_lshl_add_u32 v140, s28, 8, v146
	v_lshl_add_u32 v140, v142, 12, v140
	v_lshlrev_b32_e32 v140, 1, v140
	v_add_u32_e32 v141, 0x20000, v140
	v_add_u32_e32 v142, 0x40000, v140
	v_add_u32_e32 v143, 0x60000, v140
	v_add_u32_e32 v150, 0x100000, v140
	v_add_u32_e32 v151, 0x120000, v140
	v_add_u32_e32 v152, 0x140000, v140
	v_add_u32_e32 v153, 0x160000, v140
	v_mbcnt_lo_u32_b32 v222, -1, 0
	v_mbcnt_hi_u32_b32 v222, -1, v222
	v_bfe_u32 v222, v222, 4, 1
	v_mul_u32_u24_e32 v222, 24, v222
	v_add_u32_e32 v223, v140, v222
	v_add_u32_e32 v224, v141, v222
	v_add_u32_e32 v225, v142, v222
	v_add_u32_e32 v226, v143, v222
	v_add_u32_e32 v227, v150, v222
	v_add_u32_e32 v228, v151, v222
	v_add_u32_e32 v229, v152, v222
	v_add_u32_e32 v230, v153, v222
	global_load_dwordx4 v[154:157], v223, s[50:51]
	global_load_dwordx4 v[158:161], v223, s[50:51] offset:256
	global_load_dwordx4 v[162:165], v224, s[50:51]
	global_load_dwordx4 v[166:169], v224, s[50:51] offset:256
	global_load_dwordx4 v[170:173], v225, s[50:51]
	global_load_dwordx4 v[174:177], v225, s[50:51] offset:256
	global_load_dwordx4 v[178:181], v226, s[50:51]
	global_load_dwordx4 v[182:185], v226, s[50:51] offset:256
	global_load_dwordx4 v[186:189], v227, s[50:51]
	global_load_dwordx4 v[194:197], v227, s[50:51] offset:256
	global_load_dwordx4 v[198:201], v228, s[50:51]
	global_load_dwordx4 v[202:205], v228, s[50:51] offset:256
	global_load_dwordx4 v[206:209], v229, s[50:51]
	global_load_dwordx4 v[210:213], v229, s[50:51] offset:256
	global_load_dwordx4 v[214:217], v230, s[50:51]
	global_load_dwordx4 v[218:221], v230, s[50:51] offset:256
	s_waitcnt vmcnt(15)
	v_permlane16_swap_b32_e32 v154, v156
	v_permlane16_swap_b32_e32 v155, v157
	v_lshlrev_b32_e32 v190, 16, v154
	v_and_b32_e32 v191, 0xffff0000, v154
	v_lshlrev_b32_e32 v154, 16, v155
	v_and_b32_e32 v155, 0xffff0000, v155
	v_pk_fma_f32 v[154:155], v[154:155], s[16:17], v[126:127] op_sel_hi:[1,0,1]
	v_pk_fma_f32 v[190:191], v[190:191], s[16:17], v[124:125] op_sel_hi:[1,0,1]
	s_nop 0
	v_cvt_pk_bf16_f32 v155, v154, v155
	v_cvt_pk_bf16_f32 v154, v190, v191
	v_lshlrev_b32_e32 v190, 16, v156
	v_and_b32_e32 v191, 0xffff0000, v156
	v_lshlrev_b32_e32 v156, 16, v157
	v_and_b32_e32 v157, 0xffff0000, v157
	v_pk_fma_f32 v[156:157], v[156:157], s[16:17], v[122:123] op_sel_hi:[1,0,1]
	v_pk_fma_f32 v[190:191], v[190:191], s[16:17], v[120:121] op_sel_hi:[1,0,1]
	s_nop 0
	v_cvt_pk_bf16_f32 v157, v156, v157
	v_cvt_pk_bf16_f32 v156, v190, v191
	s_nop 1
	v_permlane16_swap_b32_e32 v154, v156
	v_permlane16_swap_b32_e32 v155, v157
	global_store_dwordx4 v223, v[154:157], s[52:53]
	s_waitcnt vmcnt(15)
	v_permlane16_swap_b32_e32 v158, v160
	v_permlane16_swap_b32_e32 v159, v161
	v_lshlrev_b32_e32 v190, 16, v158
	v_and_b32_e32 v191, 0xffff0000, v158
	v_lshlrev_b32_e32 v158, 16, v159
	v_and_b32_e32 v159, 0xffff0000, v159
	v_pk_fma_f32 v[158:159], v[158:159], s[16:17], v[94:95] op_sel_hi:[1,0,1]
	v_pk_fma_f32 v[190:191], v[190:191], s[16:17], v[92:93] op_sel_hi:[1,0,1]
	s_nop 0
	v_cvt_pk_bf16_f32 v159, v158, v159
	v_cvt_pk_bf16_f32 v158, v190, v191
	v_lshlrev_b32_e32 v190, 16, v160
	v_and_b32_e32 v191, 0xffff0000, v160
	v_lshlrev_b32_e32 v160, 16, v161
	v_and_b32_e32 v161, 0xffff0000, v161
	v_pk_fma_f32 v[160:161], v[160:161], s[16:17], v[90:91] op_sel_hi:[1,0,1]
	v_pk_fma_f32 v[190:191], v[190:191], s[16:17], v[88:89] op_sel_hi:[1,0,1]
	s_nop 0
	v_cvt_pk_bf16_f32 v161, v160, v161
	v_cvt_pk_bf16_f32 v160, v190, v191
	s_nop 1
	v_permlane16_swap_b32_e32 v158, v160
	v_permlane16_swap_b32_e32 v159, v161
	global_store_dwordx4 v223, v[158:161], s[52:53] offset:256
	s_waitcnt vmcnt(15)
	v_permlane16_swap_b32_e32 v162, v164
	v_permlane16_swap_b32_e32 v163, v165
	v_lshlrev_b32_e32 v190, 16, v162
	v_and_b32_e32 v191, 0xffff0000, v162
	v_lshlrev_b32_e32 v162, 16, v163
	v_and_b32_e32 v163, 0xffff0000, v163
	v_pk_fma_f32 v[162:163], v[162:163], s[16:17], v[118:119] op_sel_hi:[1,0,1]
	v_pk_fma_f32 v[190:191], v[190:191], s[16:17], v[116:117] op_sel_hi:[1,0,1]
	s_nop 0
	v_cvt_pk_bf16_f32 v163, v162, v163
	v_cvt_pk_bf16_f32 v162, v190, v191
	v_lshlrev_b32_e32 v190, 16, v164
	v_and_b32_e32 v191, 0xffff0000, v164
	v_lshlrev_b32_e32 v164, 16, v165
	v_and_b32_e32 v165, 0xffff0000, v165
	v_pk_fma_f32 v[164:165], v[164:165], s[16:17], v[114:115] op_sel_hi:[1,0,1]
	v_pk_fma_f32 v[190:191], v[190:191], s[16:17], v[112:113] op_sel_hi:[1,0,1]
	s_nop 0
	v_cvt_pk_bf16_f32 v165, v164, v165
	v_cvt_pk_bf16_f32 v164, v190, v191
	s_nop 1
	v_permlane16_swap_b32_e32 v162, v164
	v_permlane16_swap_b32_e32 v163, v165
	global_store_dwordx4 v224, v[162:165], s[52:53]
	s_waitcnt vmcnt(15)
	v_permlane16_swap_b32_e32 v166, v168
	v_permlane16_swap_b32_e32 v167, v169
	v_lshlrev_b32_e32 v190, 16, v166
	v_and_b32_e32 v191, 0xffff0000, v166
	v_lshlrev_b32_e32 v166, 16, v167
	v_and_b32_e32 v167, 0xffff0000, v167
	v_pk_fma_f32 v[166:167], v[166:167], s[16:17], v[86:87] op_sel_hi:[1,0,1]
	v_pk_fma_f32 v[190:191], v[190:191], s[16:17], v[84:85] op_sel_hi:[1,0,1]
	s_nop 0
	v_cvt_pk_bf16_f32 v167, v166, v167
	v_cvt_pk_bf16_f32 v166, v190, v191
	v_lshlrev_b32_e32 v190, 16, v168
	v_and_b32_e32 v191, 0xffff0000, v168
	v_lshlrev_b32_e32 v168, 16, v169
	v_and_b32_e32 v169, 0xffff0000, v169
	v_pk_fma_f32 v[168:169], v[168:169], s[16:17], v[82:83] op_sel_hi:[1,0,1]
	v_pk_fma_f32 v[190:191], v[190:191], s[16:17], v[80:81] op_sel_hi:[1,0,1]
	s_nop 0
	v_cvt_pk_bf16_f32 v169, v168, v169
	v_cvt_pk_bf16_f32 v168, v190, v191
	s_nop 1
	v_permlane16_swap_b32_e32 v166, v168
	v_permlane16_swap_b32_e32 v167, v169
	global_store_dwordx4 v224, v[166:169], s[52:53] offset:256
	s_waitcnt vmcnt(15)
; __device__ __forceinline__ unsigned pk2(float lo, float hi) { const bf16x2_t v = __builtin_convertvector((f32x2_t){lo, hi}, bf16x2_t); return __builtin_bit_cast(unsigned, v); }
; __device__ __forceinline__ float bf_lo(unsigned w) { return __uint_as_float(w << 16); }
; __device__ __forceinline__ float bf_hi(unsigned w) { return __uint_as_float(w & 0xffff0000u); }
;     __device__ __forceinline__ void row(int ai, int m, const f32x4 (&v)[2][2], const Unit& u, int wr, int wc, int fr, int fq) const {
;         const int row0 = u.pm * BM + wr * 64 + fr, col0 = u.pn * BM + wc * 32 + 4 * fq;
;         const size_t off = (size_t)(row0 + ai * HALF + m * 16) * DM + col0;
; #pragma unroll
;         for (int bj = 0; bj < 2; ++bj)
; #pragma unroll
;             for (int n = 0; n < 2; ++n) { const u32x2 rb = *(const u32x2*)(res + off + bj * HALF + n * 16);
;                 const f32x4 r = (f32x4){bf_lo(rb.x), bf_hi(rb.x), bf_lo(rb.y), bf_hi(rb.y)}; const f32x4 o = v[bj][n] + ALPHA * r;
;                 u32x2 w; w.x = pk2(o[0], o[1]); w.y = pk2(o[2], o[3]); *(u32x2*)(C + off + bj * HALF + n * 16) = w; }
;     }
	v_permlane16_swap_b32_e32 v170, v172
	v_permlane16_swap_b32_e32 v171, v173
	v_lshlrev_b32_e32 v190, 16, v170
	v_and_b32_e32 v191, 0xffff0000, v170
	v_lshlrev_b32_e32 v170, 16, v171
	v_and_b32_e32 v171, 0xffff0000, v171
	v_pk_fma_f32 v[170:171], v[170:171], s[16:17], v[110:111] op_sel_hi:[1,0,1]
	v_pk_fma_f32 v[190:191], v[190:191], s[16:17], v[108:109] op_sel_hi:[1,0,1]
	s_nop 0
	v_cvt_pk_bf16_f32 v171, v170, v171
	v_cvt_pk_bf16_f32 v170, v190, v191
	v_lshlrev_b32_e32 v190, 16, v172
	v_and_b32_e32 v191, 0xffff0000, v172
	v_lshlrev_b32_e32 v172, 16, v173
	v_and_b32_e32 v173, 0xffff0000, v173
	v_pk_fma_f32 v[172:173], v[172:173], s[16:17], v[106:107] op_sel_hi:[1,0,1]
	v_pk_fma_f32 v[190:191], v[190:191], s[16:17], v[104:105] op_sel_hi:[1,0,1]
	s_nop 0
	v_cvt_pk_bf16_f32 v173, v172, v173
	v_cvt_pk_bf16_f32 v172, v190, v191
	s_nop 1
	v_permlane16_swap_b32_e32 v170, v172
	v_permlane16_swap_b32_e32 v171, v173
	global_store_dwordx4 v225, v[170:173], s[52:53]
	s_waitcnt vmcnt(15)
	v_permlane16_swap_b32_e32 v174, v176
	v_permlane16_swap_b32_e32 v175, v177
	v_lshlrev_b32_e32 v190, 16, v174
	v_and_b32_e32 v191, 0xffff0000, v174
	v_lshlrev_b32_e32 v174, 16, v175
	v_and_b32_e32 v175, 0xffff0000, v175
	v_pk_fma_f32 v[174:175], v[174:175], s[16:17], v[78:79] op_sel_hi:[1,0,1]
	v_pk_fma_f32 v[190:191], v[190:191], s[16:17], v[76:77] op_sel_hi:[1,0,1]
	s_nop 0
	v_cvt_pk_bf16_f32 v175, v174, v175
	v_cvt_pk_bf16_f32 v174, v190, v191
	v_lshlrev_b32_e32 v190, 16, v176
	v_and_b32_e32 v191, 0xffff0000, v176
	v_lshlrev_b32_e32 v176, 16, v177
	v_and_b32_e32 v177, 0xffff0000, v177
	v_pk_fma_f32 v[176:177], v[176:177], s[16:17], v[74:75] op_sel_hi:[1,0,1]
	v_pk_fma_f32 v[190:191], v[190:191], s[16:17], v[72:73] op_sel_hi:[1,0,1]
	s_nop 0
	v_cvt_pk_bf16_f32 v177, v176, v177
	v_cvt_pk_bf16_f32 v176, v190, v191
	s_nop 1
	v_permlane16_swap_b32_e32 v174, v176
	v_permlane16_swap_b32_e32 v175, v177
	global_store_dwordx4 v225, v[174:177], s[52:53] offset:256
	s_waitcnt vmcnt(15)
	v_permlane16_swap_b32_e32 v178, v180
	v_permlane16_swap_b32_e32 v179, v181
	v_lshlrev_b32_e32 v190, 16, v178
	v_and_b32_e32 v191, 0xffff0000, v178
	v_lshlrev_b32_e32 v178, 16, v179
	v_and_b32_e32 v179, 0xffff0000, v179
	v_pk_fma_f32 v[178:179], v[178:179], s[16:17], v[102:103] op_sel_hi:[1,0,1]
	v_pk_fma_f32 v[190:191], v[190:191], s[16:17], v[100:101] op_sel_hi:[1,0,1]
	s_nop 0
	v_cvt_pk_bf16_f32 v179, v178, v179
	v_cvt_pk_bf16_f32 v178, v190, v191
	v_lshlrev_b32_e32 v190, 16, v180
	v_and_b32_e32 v191, 0xffff0000, v180
	v_lshlrev_b32_e32 v180, 16, v181
	v_and_b32_e32 v181, 0xffff0000, v181
	v_pk_fma_f32 v[180:181], v[180:181], s[16:17], v[98:99] op_sel_hi:[1,0,1]
	v_pk_fma_f32 v[190:191], v[190:191], s[16:17], v[96:97] op_sel_hi:[1,0,1]
	s_nop 0
	v_cvt_pk_bf16_f32 v181, v180, v181
	v_cvt_pk_bf16_f32 v180, v190, v191
	s_nop 1
	v_permlane16_swap_b32_e32 v178, v180
	v_permlane16_swap_b32_e32 v179, v181
	global_store_dwordx4 v226, v[178:181], s[52:53]
	s_waitcnt vmcnt(15)
	v_permlane16_swap_b32_e32 v182, v184
	v_permlane16_swap_b32_e32 v183, v185
	v_lshlrev_b32_e32 v190, 16, v182
	v_and_b32_e32 v191, 0xffff0000, v182
	v_lshlrev_b32_e32 v182, 16, v183
	v_and_b32_e32 v183, 0xffff0000, v183
	v_pk_fma_f32 v[182:183], v[182:183], s[16:17], v[70:71] op_sel_hi:[1,0,1]
	v_pk_fma_f32 v[190:191], v[190:191], s[16:17], v[68:69] op_sel_hi:[1,0,1]
	s_nop 0
	v_cvt_pk_bf16_f32 v183, v182, v183
	v_cvt_pk_bf16_f32 v182, v190, v191
	v_lshlrev_b32_e32 v190, 16, v184
	v_and_b32_e32 v191, 0xffff0000, v184
	v_lshlrev_b32_e32 v184, 16, v185
	v_and_b32_e32 v185, 0xffff0000, v185
	v_pk_fma_f32 v[184:185], v[184:185], s[16:17], v[66:67] op_sel_hi:[1,0,1]
	v_pk_fma_f32 v[190:191], v[190:191], s[16:17], v[64:65] op_sel_hi:[1,0,1]
	s_nop 0
	v_cvt_pk_bf16_f32 v185, v184, v185
	v_cvt_pk_bf16_f32 v184, v190, v191
	s_nop 1
	v_permlane16_swap_b32_e32 v182, v184
	v_permlane16_swap_b32_e32 v183, v185
	global_store_dwordx4 v226, v[182:185], s[52:53] offset:256
	s_waitcnt vmcnt(15)
	v_permlane16_swap_b32_e32 v186, v188
	v_permlane16_swap_b32_e32 v187, v189
	v_lshlrev_b32_e32 v190, 16, v186
	v_and_b32_e32 v191, 0xffff0000, v186
	v_lshlrev_b32_e32 v186, 16, v187
	v_and_b32_e32 v187, 0xffff0000, v187
	v_pk_fma_f32 v[186:187], v[186:187], s[16:17], v[62:63] op_sel_hi:[1,0,1]
	v_pk_fma_f32 v[190:191], v[190:191], s[16:17], v[60:61] op_sel_hi:[1,0,1]
	s_nop 0
	v_cvt_pk_bf16_f32 v187, v186, v187
	v_cvt_pk_bf16_f32 v186, v190, v191
	v_lshlrev_b32_e32 v190, 16, v188
	v_and_b32_e32 v191, 0xffff0000, v188
	v_lshlrev_b32_e32 v188, 16, v189
	v_and_b32_e32 v189, 0xffff0000, v189
	v_pk_fma_f32 v[188:189], v[188:189], s[16:17], v[58:59] op_sel_hi:[1,0,1]
	v_pk_fma_f32 v[190:191], v[190:191], s[16:17], v[56:57] op_sel_hi:[1,0,1]
	s_nop 0
	v_cvt_pk_bf16_f32 v189, v188, v189
	v_cvt_pk_bf16_f32 v188, v190, v191
	s_nop 1
	v_permlane16_swap_b32_e32 v186, v188
	v_permlane16_swap_b32_e32 v187, v189
	global_store_dwordx4 v227, v[186:189], s[52:53]
	s_waitcnt vmcnt(15)
	v_permlane16_swap_b32_e32 v194, v196
	v_permlane16_swap_b32_e32 v195, v197
	v_lshlrev_b32_e32 v190, 16, v194
	v_and_b32_e32 v191, 0xffff0000, v194
	v_lshlrev_b32_e32 v194, 16, v195
	v_and_b32_e32 v195, 0xffff0000, v195
	v_pk_fma_f32 v[194:195], v[194:195], s[16:17], v[30:31] op_sel_hi:[1,0,1]
	v_pk_fma_f32 v[190:191], v[190:191], s[16:17], v[28:29] op_sel_hi:[1,0,1]
	s_nop 0
	v_cvt_pk_bf16_f32 v195, v194, v195
	v_cvt_pk_bf16_f32 v194, v190, v191
	v_lshlrev_b32_e32 v190, 16, v196
	v_and_b32_e32 v191, 0xffff0000, v196
	v_lshlrev_b32_e32 v196, 16, v197
	v_and_b32_e32 v197, 0xffff0000, v197
	v_pk_fma_f32 v[196:197], v[196:197], s[16:17], v[26:27] op_sel_hi:[1,0,1]
	v_pk_fma_f32 v[190:191], v[190:191], s[16:17], v[24:25] op_sel_hi:[1,0,1]
	s_nop 0
	v_cvt_pk_bf16_f32 v197, v196, v197
	v_cvt_pk_bf16_f32 v196, v190, v191
	s_nop 1
	v_permlane16_swap_b32_e32 v194, v196
	v_permlane16_swap_b32_e32 v195, v197
	global_store_dwordx4 v227, v[194:197], s[52:53] offset:256
	s_waitcnt vmcnt(15)
; __device__ __forceinline__ unsigned pk2(float lo, float hi) { const bf16x2_t v = __builtin_convertvector((f32x2_t){lo, hi}, bf16x2_t); return __builtin_bit_cast(unsigned, v); }
; __device__ __forceinline__ float bf_lo(unsigned w) { return __uint_as_float(w << 16); }
; __device__ __forceinline__ float bf_hi(unsigned w) { return __uint_as_float(w & 0xffff0000u); }
;     __device__ __forceinline__ void row(int ai, int m, const f32x4 (&v)[2][2], const Unit& u, int wr, int wc, int fr, int fq) const {
;         const int row0 = u.pm * BM + wr * 64 + fr, col0 = u.pn * BM + wc * 32 + 4 * fq;
;         const size_t off = (size_t)(row0 + ai * HALF + m * 16) * DM + col0;
; #pragma unroll
;         for (int bj = 0; bj < 2; ++bj)
; #pragma unroll
;             for (int n = 0; n < 2; ++n) { const u32x2 rb = *(const u32x2*)(res + off + bj * HALF + n * 16);
;                 const f32x4 r = (f32x4){bf_lo(rb.x), bf_hi(rb.x), bf_lo(rb.y), bf_hi(rb.y)}; const f32x4 o = v[bj][n] + ALPHA * r;
;                 u32x2 w; w.x = pk2(o[0], o[1]); w.y = pk2(o[2], o[3]); *(u32x2*)(C + off + bj * HALF + n * 16) = w; }
;     }
	v_permlane16_swap_b32_e32 v198, v200
	v_permlane16_swap_b32_e32 v199, v201
	v_lshlrev_b32_e32 v190, 16, v198
	v_and_b32_e32 v191, 0xffff0000, v198
	v_lshlrev_b32_e32 v198, 16, v199
	v_and_b32_e32 v199, 0xffff0000, v199
	v_pk_fma_f32 v[198:199], v[198:199], s[16:17], v[54:55] op_sel_hi:[1,0,1]
	v_pk_fma_f32 v[190:191], v[190:191], s[16:17], v[52:53] op_sel_hi:[1,0,1]
	s_nop 0
	v_cvt_pk_bf16_f32 v199, v198, v199
	v_cvt_pk_bf16_f32 v198, v190, v191
	v_lshlrev_b32_e32 v190, 16, v200
	v_and_b32_e32 v191, 0xffff0000, v200
	v_lshlrev_b32_e32 v200, 16, v201
	v_and_b32_e32 v201, 0xffff0000, v201
	v_pk_fma_f32 v[200:201], v[200:201], s[16:17], v[50:51] op_sel_hi:[1,0,1]
	v_pk_fma_f32 v[190:191], v[190:191], s[16:17], v[48:49] op_sel_hi:[1,0,1]
	s_nop 0
	v_cvt_pk_bf16_f32 v201, v200, v201
	v_cvt_pk_bf16_f32 v200, v190, v191
	s_nop 1
	v_permlane16_swap_b32_e32 v198, v200
	v_permlane16_swap_b32_e32 v199, v201
	global_store_dwordx4 v228, v[198:201], s[52:53]
	s_waitcnt vmcnt(15)
	v_permlane16_swap_b32_e32 v202, v204
	v_permlane16_swap_b32_e32 v203, v205
	v_lshlrev_b32_e32 v190, 16, v202
	v_and_b32_e32 v191, 0xffff0000, v202
	v_lshlrev_b32_e32 v202, 16, v203
	v_and_b32_e32 v203, 0xffff0000, v203
	v_pk_fma_f32 v[202:203], v[202:203], s[16:17], v[22:23] op_sel_hi:[1,0,1]
	v_pk_fma_f32 v[190:191], v[190:191], s[16:17], v[20:21] op_sel_hi:[1,0,1]
	s_nop 0
	v_cvt_pk_bf16_f32 v203, v202, v203
	v_cvt_pk_bf16_f32 v202, v190, v191
	v_lshlrev_b32_e32 v190, 16, v204
	v_and_b32_e32 v191, 0xffff0000, v204
	v_lshlrev_b32_e32 v204, 16, v205
	v_and_b32_e32 v205, 0xffff0000, v205
	v_pk_fma_f32 v[204:205], v[204:205], s[16:17], v[18:19] op_sel_hi:[1,0,1]
	v_pk_fma_f32 v[190:191], v[190:191], s[16:17], v[16:17] op_sel_hi:[1,0,1]
	s_nop 0
	v_cvt_pk_bf16_f32 v205, v204, v205
	v_cvt_pk_bf16_f32 v204, v190, v191
	s_nop 1
	v_permlane16_swap_b32_e32 v202, v204
	v_permlane16_swap_b32_e32 v203, v205
	global_store_dwordx4 v228, v[202:205], s[52:53] offset:256
	s_waitcnt vmcnt(15)
	v_permlane16_swap_b32_e32 v206, v208
	v_permlane16_swap_b32_e32 v207, v209
	v_lshlrev_b32_e32 v190, 16, v206
	v_and_b32_e32 v191, 0xffff0000, v206
	v_lshlrev_b32_e32 v206, 16, v207
	v_and_b32_e32 v207, 0xffff0000, v207
	v_pk_fma_f32 v[206:207], v[206:207], s[16:17], v[46:47] op_sel_hi:[1,0,1]
	v_pk_fma_f32 v[190:191], v[190:191], s[16:17], v[44:45] op_sel_hi:[1,0,1]
	s_nop 0
	v_cvt_pk_bf16_f32 v207, v206, v207
	v_cvt_pk_bf16_f32 v206, v190, v191
	v_lshlrev_b32_e32 v190, 16, v208
	v_and_b32_e32 v191, 0xffff0000, v208
	v_lshlrev_b32_e32 v208, 16, v209
	v_and_b32_e32 v209, 0xffff0000, v209
	v_pk_fma_f32 v[208:209], v[208:209], s[16:17], v[42:43] op_sel_hi:[1,0,1]
	v_pk_fma_f32 v[190:191], v[190:191], s[16:17], v[40:41] op_sel_hi:[1,0,1]
	s_nop 0
	v_cvt_pk_bf16_f32 v209, v208, v209
	v_cvt_pk_bf16_f32 v208, v190, v191
	s_nop 1
	v_permlane16_swap_b32_e32 v206, v208
	v_permlane16_swap_b32_e32 v207, v209
	global_store_dwordx4 v229, v[206:209], s[52:53]
	s_waitcnt vmcnt(15)
	v_permlane16_swap_b32_e32 v210, v212
	v_permlane16_swap_b32_e32 v211, v213
	v_lshlrev_b32_e32 v190, 16, v210
	v_and_b32_e32 v191, 0xffff0000, v210
	v_lshlrev_b32_e32 v210, 16, v211
	v_and_b32_e32 v211, 0xffff0000, v211
	v_pk_fma_f32 v[210:211], v[210:211], s[16:17], v[14:15] op_sel_hi:[1,0,1]
	v_pk_fma_f32 v[190:191], v[190:191], s[16:17], v[12:13] op_sel_hi:[1,0,1]
	s_nop 0
	v_cvt_pk_bf16_f32 v211, v210, v211
	v_cvt_pk_bf16_f32 v210, v190, v191
	v_lshlrev_b32_e32 v190, 16, v212
	v_and_b32_e32 v191, 0xffff0000, v212
	v_lshlrev_b32_e32 v212, 16, v213
	v_and_b32_e32 v213, 0xffff0000, v213
	v_pk_fma_f32 v[212:213], v[212:213], s[16:17], v[10:11] op_sel_hi:[1,0,1]
	v_pk_fma_f32 v[190:191], v[190:191], s[16:17], v[8:9] op_sel_hi:[1,0,1]
	s_nop 0
	v_cvt_pk_bf16_f32 v213, v212, v213
	v_cvt_pk_bf16_f32 v212, v190, v191
	s_nop 1
	v_permlane16_swap_b32_e32 v210, v212
	v_permlane16_swap_b32_e32 v211, v213
	global_store_dwordx4 v229, v[210:213], s[52:53] offset:256
	s_waitcnt vmcnt(15)
	v_permlane16_swap_b32_e32 v214, v216
	v_permlane16_swap_b32_e32 v215, v217
	v_lshlrev_b32_e32 v190, 16, v214
	v_and_b32_e32 v191, 0xffff0000, v214
	v_lshlrev_b32_e32 v214, 16, v215
	v_and_b32_e32 v215, 0xffff0000, v215
	v_pk_fma_f32 v[214:215], v[214:215], s[16:17], v[38:39] op_sel_hi:[1,0,1]
	v_pk_fma_f32 v[190:191], v[190:191], s[16:17], v[36:37] op_sel_hi:[1,0,1]
	s_nop 0
	v_cvt_pk_bf16_f32 v215, v214, v215
	v_cvt_pk_bf16_f32 v214, v190, v191
	v_lshlrev_b32_e32 v190, 16, v216
	v_and_b32_e32 v191, 0xffff0000, v216
	v_lshlrev_b32_e32 v216, 16, v217
	v_and_b32_e32 v217, 0xffff0000, v217
	v_pk_fma_f32 v[216:217], v[216:217], s[16:17], v[34:35] op_sel_hi:[1,0,1]
	v_pk_fma_f32 v[190:191], v[190:191], s[16:17], v[32:33] op_sel_hi:[1,0,1]
	s_nop 0
	v_cvt_pk_bf16_f32 v217, v216, v217
	v_cvt_pk_bf16_f32 v216, v190, v191
	s_nop 1
	v_permlane16_swap_b32_e32 v214, v216
	v_permlane16_swap_b32_e32 v215, v217
	global_store_dwordx4 v230, v[214:217], s[52:53]
	s_waitcnt vmcnt(15)
	v_permlane16_swap_b32_e32 v218, v220
	v_permlane16_swap_b32_e32 v219, v221
	v_lshlrev_b32_e32 v190, 16, v218
	v_and_b32_e32 v191, 0xffff0000, v218
	v_lshlrev_b32_e32 v218, 16, v219
	v_and_b32_e32 v219, 0xffff0000, v219
	v_pk_fma_f32 v[218:219], v[218:219], s[16:17], v[6:7] op_sel_hi:[1,0,1]
	v_pk_fma_f32 v[190:191], v[190:191], s[16:17], v[4:5] op_sel_hi:[1,0,1]
	s_nop 0
	v_cvt_pk_bf16_f32 v219, v218, v219
	v_cvt_pk_bf16_f32 v218, v190, v191
	v_lshlrev_b32_e32 v190, 16, v220
	v_and_b32_e32 v191, 0xffff0000, v220
	v_lshlrev_b32_e32 v220, 16, v221
	v_and_b32_e32 v221, 0xffff0000, v221
	v_pk_fma_f32 v[220:221], v[220:221], s[16:17], v[2:3] op_sel_hi:[1,0,1]
	v_pk_fma_f32 v[190:191], v[190:191], s[16:17], v[0:1] op_sel_hi:[1,0,1]
	s_nop 0
	v_cvt_pk_bf16_f32 v221, v220, v221
	v_cvt_pk_bf16_f32 v220, v190, v191
	s_nop 1
	v_permlane16_swap_b32_e32 v218, v220
	v_permlane16_swap_b32_e32 v219, v221
	global_store_dwordx4 v230, v[218:221], s[52:53] offset:256
	s_cbranch_execz .LBB0_909

; __device__ __forceinline__ unsigned pk2(float lo, float hi) { const bf16x2_t v = __builtin_convertvector((f32x2_t){lo, hi}, bf16x2_t); return __builtin_bit_cast(unsigned, v); }
; __device__ __forceinline__ float bf_lo(unsigned w) { return __uint_as_float(w << 16); }
; __device__ __forceinline__ float bf_hi(unsigned w) { return __uint_as_float(w & 0xffff0000u); }
;     __device__ __forceinline__ void row(int ai, int m, const f32x4 (&v)[2][2], const Unit& u, int wr, int wc, int fr, int fq) const {
;         const int row0 = u.pm * BM + wr * 64 + fr, col0 = u.pn * BM + wc * 32 + 4 * fq;
;         const size_t off = (size_t)(row0 + ai * HALF + m * 16) * DM + col0;
; #pragma unroll
;         for (int bj = 0; bj < 2; ++bj)
; #pragma unroll
;             for (int n = 0; n < 2; ++n) { const u32x2 rb = *(const u32x2*)(res + off + bj * HALF + n * 16);
;                 const f32x4 r = (f32x4){bf_lo(rb.x), bf_hi(rb.x), bf_lo(rb.y), bf_hi(rb.y)}; const f32x4 o = v[bj][n] + ALPHA * r;
;                 u32x2 w; w.x = pk2(o[0], o[1]); w.y = pk2(o[2], o[3]); *(u32x2*)(C + off + bj * HALF + n * 16) = w; }
;     }
.LBB0_1256:
	v_lshl_add_u32 v142, s90, 8, v144
	v_lshl_add_u32 v140, s89, 8, v146
	v_lshl_add_u32 v140, v142, 12, v140
	v_lshlrev_b32_e32 v140, 1, v140
	v_add_u32_e32 v141, 0x20000, v140
	v_add_u32_e32 v142, 0x40000, v140
	v_add_u32_e32 v143, 0x60000, v140
	v_add_u32_e32 v150, 0x100000, v140
	v_add_u32_e32 v151, 0x120000, v140
	v_add_u32_e32 v152, 0x140000, v140
	v_add_u32_e32 v153, 0x160000, v140
	v_mbcnt_lo_u32_b32 v222, -1, 0
	v_mbcnt_hi_u32_b32 v222, -1, v222
	v_bfe_u32 v222, v222, 4, 1
	v_mul_u32_u24_e32 v222, 24, v222
	v_add_u32_e32 v223, v140, v222
	v_add_u32_e32 v224, v141, v222
	v_add_u32_e32 v225, v142, v222
	v_add_u32_e32 v226, v143, v222
	v_add_u32_e32 v227, v150, v222
	v_add_u32_e32 v228, v151, v222
	v_add_u32_e32 v229, v152, v222
	v_add_u32_e32 v230, v153, v222
	global_load_dwordx4 v[154:157], v223, s[50:51]
	global_load_dwordx4 v[158:161], v223, s[50:51] offset:256
	global_load_dwordx4 v[162:165], v224, s[50:51]
	global_load_dwordx4 v[166:169], v224, s[50:51] offset:256
	global_load_dwordx4 v[170:173], v225, s[50:51]
	global_load_dwordx4 v[174:177], v225, s[50:51] offset:256
	global_load_dwordx4 v[178:181], v226, s[50:51]
	global_load_dwordx4 v[182:185], v226, s[50:51] offset:256
	global_load_dwordx4 v[186:189], v227, s[50:51]
	global_load_dwordx4 v[194:197], v227, s[50:51] offset:256
	global_load_dwordx4 v[198:201], v228, s[50:51]
	global_load_dwordx4 v[202:205], v228, s[50:51] offset:256
	global_load_dwordx4 v[206:209], v229, s[50:51]
	global_load_dwordx4 v[210:213], v229, s[50:51] offset:256
	global_load_dwordx4 v[214:217], v230, s[50:51]
	global_load_dwordx4 v[218:221], v230, s[50:51] offset:256
	s_waitcnt vmcnt(15)
	v_permlane16_swap_b32_e32 v154, v156
	v_permlane16_swap_b32_e32 v155, v157
	v_lshlrev_b32_e32 v190, 16, v154
	v_and_b32_e32 v191, 0xffff0000, v154
	v_lshlrev_b32_e32 v154, 16, v155
	v_and_b32_e32 v155, 0xffff0000, v155
	v_pk_fma_f32 v[154:155], v[154:155], s[18:19], v[126:127] op_sel_hi:[1,0,1]
	v_pk_fma_f32 v[190:191], v[190:191], s[18:19], v[124:125] op_sel_hi:[1,0,1]
	s_nop 0
	v_cvt_pk_bf16_f32 v155, v154, v155
	v_cvt_pk_bf16_f32 v154, v190, v191
	v_lshlrev_b32_e32 v190, 16, v156
	v_and_b32_e32 v191, 0xffff0000, v156
	v_lshlrev_b32_e32 v156, 16, v157
	v_and_b32_e32 v157, 0xffff0000, v157
	v_pk_fma_f32 v[156:157], v[156:157], s[18:19], v[122:123] op_sel_hi:[1,0,1]
	v_pk_fma_f32 v[190:191], v[190:191], s[18:19], v[120:121] op_sel_hi:[1,0,1]
	s_nop 0
	v_cvt_pk_bf16_f32 v157, v156, v157
	v_cvt_pk_bf16_f32 v156, v190, v191
	s_nop 1
	v_permlane16_swap_b32_e32 v154, v156
	v_permlane16_swap_b32_e32 v155, v157
	global_store_dwordx4 v223, v[154:157], s[52:53]
	s_waitcnt vmcnt(15)
	v_permlane16_swap_b32_e32 v158, v160
	v_permlane16_swap_b32_e32 v159, v161
	v_lshlrev_b32_e32 v190, 16, v158
	v_and_b32_e32 v191, 0xffff0000, v158
	v_lshlrev_b32_e32 v158, 16, v159
	v_and_b32_e32 v159, 0xffff0000, v159
	v_pk_fma_f32 v[158:159], v[158:159], s[18:19], v[94:95] op_sel_hi:[1,0,1]
	v_pk_fma_f32 v[190:191], v[190:191], s[18:19], v[92:93] op_sel_hi:[1,0,1]
	s_nop 0
	v_cvt_pk_bf16_f32 v159, v158, v159
	v_cvt_pk_bf16_f32 v158, v190, v191
	v_lshlrev_b32_e32 v190, 16, v160
	v_and_b32_e32 v191, 0xffff0000, v160
	v_lshlrev_b32_e32 v160, 16, v161
	v_and_b32_e32 v161, 0xffff0000, v161
	v_pk_fma_f32 v[160:161], v[160:161], s[18:19], v[90:91] op_sel_hi:[1,0,1]
	v_pk_fma_f32 v[190:191], v[190:191], s[18:19], v[88:89] op_sel_hi:[1,0,1]
	s_nop 0
	v_cvt_pk_bf16_f32 v161, v160, v161
	v_cvt_pk_bf16_f32 v160, v190, v191
	s_nop 1
	v_permlane16_swap_b32_e32 v158, v160
	v_permlane16_swap_b32_e32 v159, v161
	global_store_dwordx4 v223, v[158:161], s[52:53] offset:256
	s_waitcnt vmcnt(15)
	v_permlane16_swap_b32_e32 v162, v164
	v_permlane16_swap_b32_e32 v163, v165
	v_lshlrev_b32_e32 v190, 16, v162
	v_and_b32_e32 v191, 0xffff0000, v162
	v_lshlrev_b32_e32 v162, 16, v163
	v_and_b32_e32 v163, 0xffff0000, v163
	v_pk_fma_f32 v[162:163], v[162:163], s[18:19], v[118:119] op_sel_hi:[1,0,1]
	v_pk_fma_f32 v[190:191], v[190:191], s[18:19], v[116:117] op_sel_hi:[1,0,1]
	s_nop 0
	v_cvt_pk_bf16_f32 v163, v162, v163
	v_cvt_pk_bf16_f32 v162, v190, v191
	v_lshlrev_b32_e32 v190, 16, v164
	v_and_b32_e32 v191, 0xffff0000, v164
	v_lshlrev_b32_e32 v164, 16, v165
	v_and_b32_e32 v165, 0xffff0000, v165
	v_pk_fma_f32 v[164:165], v[164:165], s[18:19], v[114:115] op_sel_hi:[1,0,1]
	v_pk_fma_f32 v[190:191], v[190:191], s[18:19], v[112:113] op_sel_hi:[1,0,1]
	s_nop 0
	v_cvt_pk_bf16_f32 v165, v164, v165
	v_cvt_pk_bf16_f32 v164, v190, v191
	s_nop 1
	v_permlane16_swap_b32_e32 v162, v164
	v_permlane16_swap_b32_e32 v163, v165
	global_store_dwordx4 v224, v[162:165], s[52:53]
	s_waitcnt vmcnt(15)
	v_permlane16_swap_b32_e32 v166, v168
	v_permlane16_swap_b32_e32 v167, v169
	v_lshlrev_b32_e32 v190, 16, v166
	v_and_b32_e32 v191, 0xffff0000, v166
	v_lshlrev_b32_e32 v166, 16, v167
	v_and_b32_e32 v167, 0xffff0000, v167
	v_pk_fma_f32 v[166:167], v[166:167], s[18:19], v[86:87] op_sel_hi:[1,0,1]
	v_pk_fma_f32 v[190:191], v[190:191], s[18:19], v[84:85] op_sel_hi:[1,0,1]
	s_nop 0
	v_cvt_pk_bf16_f32 v167, v166, v167
	v_cvt_pk_bf16_f32 v166, v190, v191
	v_lshlrev_b32_e32 v190, 16, v168
	v_and_b32_e32 v191, 0xffff0000, v168
	v_lshlrev_b32_e32 v168, 16, v169
	v_and_b32_e32 v169, 0xffff0000, v169
	v_pk_fma_f32 v[168:169], v[168:169], s[18:19], v[82:83] op_sel_hi:[1,0,1]
	v_pk_fma_f32 v[190:191], v[190:191], s[18:19], v[80:81] op_sel_hi:[1,0,1]
	s_nop 0
	v_cvt_pk_bf16_f32 v169, v168, v169
	v_cvt_pk_bf16_f32 v168, v190, v191
	s_nop 1
	v_permlane16_swap_b32_e32 v166, v168
	v_permlane16_swap_b32_e32 v167, v169
	global_store_dwordx4 v224, v[166:169], s[52:53] offset:256
	s_waitcnt vmcnt(15)
; __device__ __forceinline__ unsigned pk2(float lo, float hi) { const bf16x2_t v = __builtin_convertvector((f32x2_t){lo, hi}, bf16x2_t); return __builtin_bit_cast(unsigned, v); }
; __device__ __forceinline__ float bf_lo(unsigned w) { return __uint_as_float(w << 16); }
; __device__ __forceinline__ float bf_hi(unsigned w) { return __uint_as_float(w & 0xffff0000u); }
;     __device__ __forceinline__ void row(int ai, int m, const f32x4 (&v)[2][2], const Unit& u, int wr, int wc, int fr, int fq) const {
;         const int row0 = u.pm * BM + wr * 64 + fr, col0 = u.pn * BM + wc * 32 + 4 * fq;
;         const size_t off = (size_t)(row0 + ai * HALF + m * 16) * DM + col0;
; #pragma unroll
;         for (int bj = 0; bj < 2; ++bj)
; #pragma unroll
;             for (int n = 0; n < 2; ++n) { const u32x2 rb = *(const u32x2*)(res + off + bj * HALF + n * 16);
;                 const f32x4 r = (f32x4){bf_lo(rb.x), bf_hi(rb.x), bf_lo(rb.y), bf_hi(rb.y)}; const f32x4 o = v[bj][n] + ALPHA * r;
;                 u32x2 w; w.x = pk2(o[0], o[1]); w.y = pk2(o[2], o[3]); *(u32x2*)(C + off + bj * HALF + n * 16) = w; }
;     }
	v_permlane16_swap_b32_e32 v170, v172
	v_permlane16_swap_b32_e32 v171, v173
	v_lshlrev_b32_e32 v190, 16, v170
	v_and_b32_e32 v191, 0xffff0000, v170
	v_lshlrev_b32_e32 v170, 16, v171
	v_and_b32_e32 v171, 0xffff0000, v171
	v_pk_fma_f32 v[170:171], v[170:171], s[18:19], v[110:111] op_sel_hi:[1,0,1]
	v_pk_fma_f32 v[190:191], v[190:191], s[18:19], v[108:109] op_sel_hi:[1,0,1]
	s_nop 0
	v_cvt_pk_bf16_f32 v171, v170, v171
	v_cvt_pk_bf16_f32 v170, v190, v191
	v_lshlrev_b32_e32 v190, 16, v172
	v_and_b32_e32 v191, 0xffff0000, v172
	v_lshlrev_b32_e32 v172, 16, v173
	v_and_b32_e32 v173, 0xffff0000, v173
	v_pk_fma_f32 v[172:173], v[172:173], s[18:19], v[106:107] op_sel_hi:[1,0,1]
	v_pk_fma_f32 v[190:191], v[190:191], s[18:19], v[104:105] op_sel_hi:[1,0,1]
	s_nop 0
	v_cvt_pk_bf16_f32 v173, v172, v173
	v_cvt_pk_bf16_f32 v172, v190, v191
	s_nop 1
	v_permlane16_swap_b32_e32 v170, v172
	v_permlane16_swap_b32_e32 v171, v173
	global_store_dwordx4 v225, v[170:173], s[52:53]
	s_waitcnt vmcnt(15)
	v_permlane16_swap_b32_e32 v174, v176
	v_permlane16_swap_b32_e32 v175, v177
	v_lshlrev_b32_e32 v190, 16, v174
	v_and_b32_e32 v191, 0xffff0000, v174
	v_lshlrev_b32_e32 v174, 16, v175
	v_and_b32_e32 v175, 0xffff0000, v175
	v_pk_fma_f32 v[174:175], v[174:175], s[18:19], v[78:79] op_sel_hi:[1,0,1]
	v_pk_fma_f32 v[190:191], v[190:191], s[18:19], v[76:77] op_sel_hi:[1,0,1]
	s_nop 0
	v_cvt_pk_bf16_f32 v175, v174, v175
	v_cvt_pk_bf16_f32 v174, v190, v191
	v_lshlrev_b32_e32 v190, 16, v176
	v_and_b32_e32 v191, 0xffff0000, v176
	v_lshlrev_b32_e32 v176, 16, v177
	v_and_b32_e32 v177, 0xffff0000, v177
	v_pk_fma_f32 v[176:177], v[176:177], s[18:19], v[74:75] op_sel_hi:[1,0,1]
	v_pk_fma_f32 v[190:191], v[190:191], s[18:19], v[72:73] op_sel_hi:[1,0,1]
	s_nop 0
	v_cvt_pk_bf16_f32 v177, v176, v177
	v_cvt_pk_bf16_f32 v176, v190, v191
	s_nop 1
	v_permlane16_swap_b32_e32 v174, v176
	v_permlane16_swap_b32_e32 v175, v177
	global_store_dwordx4 v225, v[174:177], s[52:53] offset:256
	s_waitcnt vmcnt(15)
	v_permlane16_swap_b32_e32 v178, v180
	v_permlane16_swap_b32_e32 v179, v181
	v_lshlrev_b32_e32 v190, 16, v178
	v_and_b32_e32 v191, 0xffff0000, v178
	v_lshlrev_b32_e32 v178, 16, v179
	v_and_b32_e32 v179, 0xffff0000, v179
	v_pk_fma_f32 v[178:179], v[178:179], s[18:19], v[102:103] op_sel_hi:[1,0,1]
	v_pk_fma_f32 v[190:191], v[190:191], s[18:19], v[100:101] op_sel_hi:[1,0,1]
	s_nop 0
	v_cvt_pk_bf16_f32 v179, v178, v179
	v_cvt_pk_bf16_f32 v178, v190, v191
	v_lshlrev_b32_e32 v190, 16, v180
	v_and_b32_e32 v191, 0xffff0000, v180
	v_lshlrev_b32_e32 v180, 16, v181
	v_and_b32_e32 v181, 0xffff0000, v181
	v_pk_fma_f32 v[180:181], v[180:181], s[18:19], v[98:99] op_sel_hi:[1,0,1]
	v_pk_fma_f32 v[190:191], v[190:191], s[18:19], v[96:97] op_sel_hi:[1,0,1]
	s_nop 0
	v_cvt_pk_bf16_f32 v181, v180, v181
	v_cvt_pk_bf16_f32 v180, v190, v191
	s_nop 1
	v_permlane16_swap_b32_e32 v178, v180
	v_permlane16_swap_b32_e32 v179, v181
	global_store_dwordx4 v226, v[178:181], s[52:53]
	s_waitcnt vmcnt(15)
	v_permlane16_swap_b32_e32 v182, v184
	v_permlane16_swap_b32_e32 v183, v185
	v_lshlrev_b32_e32 v190, 16, v182
	v_and_b32_e32 v191, 0xffff0000, v182
	v_lshlrev_b32_e32 v182, 16, v183
	v_and_b32_e32 v183, 0xffff0000, v183
	v_pk_fma_f32 v[182:183], v[182:183], s[18:19], v[70:71] op_sel_hi:[1,0,1]
	v_pk_fma_f32 v[190:191], v[190:191], s[18:19], v[68:69] op_sel_hi:[1,0,1]
	s_nop 0
	v_cvt_pk_bf16_f32 v183, v182, v183
	v_cvt_pk_bf16_f32 v182, v190, v191
	v_lshlrev_b32_e32 v190, 16, v184
	v_and_b32_e32 v191, 0xffff0000, v184
	v_lshlrev_b32_e32 v184, 16, v185
	v_and_b32_e32 v185, 0xffff0000, v185
	v_pk_fma_f32 v[184:185], v[184:185], s[18:19], v[66:67] op_sel_hi:[1,0,1]
	v_pk_fma_f32 v[190:191], v[190:191], s[18:19], v[64:65] op_sel_hi:[1,0,1]
	s_nop 0
	v_cvt_pk_bf16_f32 v185, v184, v185
	v_cvt_pk_bf16_f32 v184, v190, v191
	s_nop 1
	v_permlane16_swap_b32_e32 v182, v184
	v_permlane16_swap_b32_e32 v183, v185
	global_store_dwordx4 v226, v[182:185], s[52:53] offset:256
	s_waitcnt vmcnt(15)
	v_permlane16_swap_b32_e32 v186, v188
	v_permlane16_swap_b32_e32 v187, v189
	v_lshlrev_b32_e32 v190, 16, v186
	v_and_b32_e32 v191, 0xffff0000, v186
	v_lshlrev_b32_e32 v186, 16, v187
	v_and_b32_e32 v187, 0xffff0000, v187
	v_pk_fma_f32 v[186:187], v[186:187], s[18:19], v[62:63] op_sel_hi:[1,0,1]
	v_pk_fma_f32 v[190:191], v[190:191], s[18:19], v[60:61] op_sel_hi:[1,0,1]
	s_nop 0
	v_cvt_pk_bf16_f32 v187, v186, v187
	v_cvt_pk_bf16_f32 v186, v190, v191
	v_lshlrev_b32_e32 v190, 16, v188
	v_and_b32_e32 v191, 0xffff0000, v188
	v_lshlrev_b32_e32 v188, 16, v189
	v_and_b32_e32 v189, 0xffff0000, v189
	v_pk_fma_f32 v[188:189], v[188:189], s[18:19], v[58:59] op_sel_hi:[1,0,1]
	v_pk_fma_f32 v[190:191], v[190:191], s[18:19], v[56:57] op_sel_hi:[1,0,1]
	s_nop 0
	v_cvt_pk_bf16_f32 v189, v188, v189
	v_cvt_pk_bf16_f32 v188, v190, v191
	s_nop 1
	v_permlane16_swap_b32_e32 v186, v188
	v_permlane16_swap_b32_e32 v187, v189
	global_store_dwordx4 v227, v[186:189], s[52:53]
	s_waitcnt vmcnt(15)
	v_permlane16_swap_b32_e32 v194, v196
	v_permlane16_swap_b32_e32 v195, v197
	v_lshlrev_b32_e32 v190, 16, v194
	v_and_b32_e32 v191, 0xffff0000, v194
	v_lshlrev_b32_e32 v194, 16, v195
	v_and_b32_e32 v195, 0xffff0000, v195
	v_pk_fma_f32 v[194:195], v[194:195], s[18:19], v[30:31] op_sel_hi:[1,0,1]
	v_pk_fma_f32 v[190:191], v[190:191], s[18:19], v[28:29] op_sel_hi:[1,0,1]
	s_nop 0
	v_cvt_pk_bf16_f32 v195, v194, v195
	v_cvt_pk_bf16_f32 v194, v190, v191
	v_lshlrev_b32_e32 v190, 16, v196
	v_and_b32_e32 v191, 0xffff0000, v196
	v_lshlrev_b32_e32 v196, 16, v197
	v_and_b32_e32 v197, 0xffff0000, v197
	v_pk_fma_f32 v[196:197], v[196:197], s[18:19], v[26:27] op_sel_hi:[1,0,1]
	v_pk_fma_f32 v[190:191], v[190:191], s[18:19], v[24:25] op_sel_hi:[1,0,1]
	s_nop 0
	v_cvt_pk_bf16_f32 v197, v196, v197
	v_cvt_pk_bf16_f32 v196, v190, v191
	s_nop 1
	v_permlane16_swap_b32_e32 v194, v196
	v_permlane16_swap_b32_e32 v195, v197
	global_store_dwordx4 v227, v[194:197], s[52:53] offset:256
	s_waitcnt vmcnt(15)
; __device__ __forceinline__ unsigned pk2(float lo, float hi) { const bf16x2_t v = __builtin_convertvector((f32x2_t){lo, hi}, bf16x2_t); return __builtin_bit_cast(unsigned, v); }
; __device__ __forceinline__ float bf_lo(unsigned w) { return __uint_as_float(w << 16); }
; __device__ __forceinline__ float bf_hi(unsigned w) { return __uint_as_float(w & 0xffff0000u); }
;     __device__ __forceinline__ void row(int ai, int m, const f32x4 (&v)[2][2], const Unit& u, int wr, int wc, int fr, int fq) const {
;         const int row0 = u.pm * BM + wr * 64 + fr, col0 = u.pn * BM + wc * 32 + 4 * fq;
;         const size_t off = (size_t)(row0 + ai * HALF + m * 16) * DM + col0;
; #pragma unroll
;         for (int bj = 0; bj < 2; ++bj)
; #pragma unroll
;             for (int n = 0; n < 2; ++n) { const u32x2 rb = *(const u32x2*)(res + off + bj * HALF + n * 16);
;                 const f32x4 r = (f32x4){bf_lo(rb.x), bf_hi(rb.x), bf_lo(rb.y), bf_hi(rb.y)}; const f32x4 o = v[bj][n] + ALPHA * r;
;                 u32x2 w; w.x = pk2(o[0], o[1]); w.y = pk2(o[2], o[3]); *(u32x2*)(C + off + bj * HALF + n * 16) = w; }
;     }
	v_permlane16_swap_b32_e32 v198, v200
	v_permlane16_swap_b32_e32 v199, v201
	v_lshlrev_b32_e32 v190, 16, v198
	v_and_b32_e32 v191, 0xffff0000, v198
	v_lshlrev_b32_e32 v198, 16, v199
	v_and_b32_e32 v199, 0xffff0000, v199
	v_pk_fma_f32 v[198:199], v[198:199], s[18:19], v[54:55] op_sel_hi:[1,0,1]
	v_pk_fma_f32 v[190:191], v[190:191], s[18:19], v[52:53] op_sel_hi:[1,0,1]
	s_nop 0
	v_cvt_pk_bf16_f32 v199, v198, v199
	v_cvt_pk_bf16_f32 v198, v190, v191
	v_lshlrev_b32_e32 v190, 16, v200
	v_and_b32_e32 v191, 0xffff0000, v200
	v_lshlrev_b32_e32 v200, 16, v201
	v_and_b32_e32 v201, 0xffff0000, v201
	v_pk_fma_f32 v[200:201], v[200:201], s[18:19], v[50:51] op_sel_hi:[1,0,1]
	v_pk_fma_f32 v[190:191], v[190:191], s[18:19], v[48:49] op_sel_hi:[1,0,1]
	s_nop 0
	v_cvt_pk_bf16_f32 v201, v200, v201
	v_cvt_pk_bf16_f32 v200, v190, v191
	s_nop 1
	v_permlane16_swap_b32_e32 v198, v200
	v_permlane16_swap_b32_e32 v199, v201
	global_store_dwordx4 v228, v[198:201], s[52:53]
	s_waitcnt vmcnt(15)
	v_permlane16_swap_b32_e32 v202, v204
	v_permlane16_swap_b32_e32 v203, v205
	v_lshlrev_b32_e32 v190, 16, v202
	v_and_b32_e32 v191, 0xffff0000, v202
	v_lshlrev_b32_e32 v202, 16, v203
	v_and_b32_e32 v203, 0xffff0000, v203
	v_pk_fma_f32 v[202:203], v[202:203], s[18:19], v[22:23] op_sel_hi:[1,0,1]
	v_pk_fma_f32 v[190:191], v[190:191], s[18:19], v[20:21] op_sel_hi:[1,0,1]
	s_nop 0
	v_cvt_pk_bf16_f32 v203, v202, v203
	v_cvt_pk_bf16_f32 v202, v190, v191
	v_lshlrev_b32_e32 v190, 16, v204
	v_and_b32_e32 v191, 0xffff0000, v204
	v_lshlrev_b32_e32 v204, 16, v205
	v_and_b32_e32 v205, 0xffff0000, v205
	v_pk_fma_f32 v[204:205], v[204:205], s[18:19], v[18:19] op_sel_hi:[1,0,1]
	v_pk_fma_f32 v[190:191], v[190:191], s[18:19], v[16:17] op_sel_hi:[1,0,1]
	s_nop 0
	v_cvt_pk_bf16_f32 v205, v204, v205
	v_cvt_pk_bf16_f32 v204, v190, v191
	s_nop 1
	v_permlane16_swap_b32_e32 v202, v204
	v_permlane16_swap_b32_e32 v203, v205
	global_store_dwordx4 v228, v[202:205], s[52:53] offset:256
	s_waitcnt vmcnt(15)
	v_permlane16_swap_b32_e32 v206, v208
	v_permlane16_swap_b32_e32 v207, v209
	v_lshlrev_b32_e32 v190, 16, v206
	v_and_b32_e32 v191, 0xffff0000, v206
	v_lshlrev_b32_e32 v206, 16, v207
	v_and_b32_e32 v207, 0xffff0000, v207
	v_pk_fma_f32 v[206:207], v[206:207], s[18:19], v[46:47] op_sel_hi:[1,0,1]
	v_pk_fma_f32 v[190:191], v[190:191], s[18:19], v[44:45] op_sel_hi:[1,0,1]
	s_nop 0
	v_cvt_pk_bf16_f32 v207, v206, v207
	v_cvt_pk_bf16_f32 v206, v190, v191
	v_lshlrev_b32_e32 v190, 16, v208
	v_and_b32_e32 v191, 0xffff0000, v208
	v_lshlrev_b32_e32 v208, 16, v209
	v_and_b32_e32 v209, 0xffff0000, v209
	v_pk_fma_f32 v[208:209], v[208:209], s[18:19], v[42:43] op_sel_hi:[1,0,1]
	v_pk_fma_f32 v[190:191], v[190:191], s[18:19], v[40:41] op_sel_hi:[1,0,1]
	s_nop 0
	v_cvt_pk_bf16_f32 v209, v208, v209
	v_cvt_pk_bf16_f32 v208, v190, v191
	s_nop 1
	v_permlane16_swap_b32_e32 v206, v208
	v_permlane16_swap_b32_e32 v207, v209
	global_store_dwordx4 v229, v[206:209], s[52:53]
	s_waitcnt vmcnt(15)
	v_permlane16_swap_b32_e32 v210, v212
	v_permlane16_swap_b32_e32 v211, v213
	v_lshlrev_b32_e32 v190, 16, v210
	v_and_b32_e32 v191, 0xffff0000, v210
	v_lshlrev_b32_e32 v210, 16, v211
	v_and_b32_e32 v211, 0xffff0000, v211
	v_pk_fma_f32 v[210:211], v[210:211], s[18:19], v[14:15] op_sel_hi:[1,0,1]
	v_pk_fma_f32 v[190:191], v[190:191], s[18:19], v[12:13] op_sel_hi:[1,0,1]
	s_nop 0
	v_cvt_pk_bf16_f32 v211, v210, v211
	v_cvt_pk_bf16_f32 v210, v190, v191
	v_lshlrev_b32_e32 v190, 16, v212
	v_and_b32_e32 v191, 0xffff0000, v212
	v_lshlrev_b32_e32 v212, 16, v213
	v_and_b32_e32 v213, 0xffff0000, v213
	v_pk_fma_f32 v[212:213], v[212:213], s[18:19], v[10:11] op_sel_hi:[1,0,1]
	v_pk_fma_f32 v[190:191], v[190:191], s[18:19], v[8:9] op_sel_hi:[1,0,1]
	s_nop 0
	v_cvt_pk_bf16_f32 v213, v212, v213
	v_cvt_pk_bf16_f32 v212, v190, v191
	s_nop 1
	v_permlane16_swap_b32_e32 v210, v212
	v_permlane16_swap_b32_e32 v211, v213
	global_store_dwordx4 v229, v[210:213], s[52:53] offset:256
	s_waitcnt vmcnt(15)
	v_permlane16_swap_b32_e32 v214, v216
	v_permlane16_swap_b32_e32 v215, v217
	v_lshlrev_b32_e32 v190, 16, v214
	v_and_b32_e32 v191, 0xffff0000, v214
	v_lshlrev_b32_e32 v214, 16, v215
	v_and_b32_e32 v215, 0xffff0000, v215
	v_pk_fma_f32 v[214:215], v[214:215], s[18:19], v[38:39] op_sel_hi:[1,0,1]
	v_pk_fma_f32 v[190:191], v[190:191], s[18:19], v[36:37] op_sel_hi:[1,0,1]
	s_nop 0
	v_cvt_pk_bf16_f32 v215, v214, v215
	v_cvt_pk_bf16_f32 v214, v190, v191
	v_lshlrev_b32_e32 v190, 16, v216
	v_and_b32_e32 v191, 0xffff0000, v216
	v_lshlrev_b32_e32 v216, 16, v217
	v_and_b32_e32 v217, 0xffff0000, v217
	v_pk_fma_f32 v[216:217], v[216:217], s[18:19], v[34:35] op_sel_hi:[1,0,1]
	v_pk_fma_f32 v[190:191], v[190:191], s[18:19], v[32:33] op_sel_hi:[1,0,1]
	s_nop 0
	v_cvt_pk_bf16_f32 v217, v216, v217
	v_cvt_pk_bf16_f32 v216, v190, v191
	s_nop 1
	v_permlane16_swap_b32_e32 v214, v216
	v_permlane16_swap_b32_e32 v215, v217
	global_store_dwordx4 v230, v[214:217], s[52:53]
	s_waitcnt vmcnt(15)
	v_permlane16_swap_b32_e32 v218, v220
	v_permlane16_swap_b32_e32 v219, v221
	v_lshlrev_b32_e32 v190, 16, v218
	v_and_b32_e32 v191, 0xffff0000, v218
	v_lshlrev_b32_e32 v218, 16, v219
	v_and_b32_e32 v219, 0xffff0000, v219
	v_pk_fma_f32 v[218:219], v[218:219], s[18:19], v[6:7] op_sel_hi:[1,0,1]
	v_pk_fma_f32 v[190:191], v[190:191], s[18:19], v[4:5] op_sel_hi:[1,0,1]
	s_nop 0
	v_cvt_pk_bf16_f32 v219, v218, v219
	v_cvt_pk_bf16_f32 v218, v190, v191
	v_lshlrev_b32_e32 v190, 16, v220
	v_and_b32_e32 v191, 0xffff0000, v220
	v_lshlrev_b32_e32 v220, 16, v221
	v_and_b32_e32 v221, 0xffff0000, v221
	v_pk_fma_f32 v[220:221], v[220:221], s[18:19], v[2:3] op_sel_hi:[1,0,1]
	v_pk_fma_f32 v[190:191], v[190:191], s[18:19], v[0:1] op_sel_hi:[1,0,1]
	s_nop 0
	v_cvt_pk_bf16_f32 v221, v220, v221
	v_cvt_pk_bf16_f32 v220, v190, v191
	s_nop 1
	v_permlane16_swap_b32_e32 v218, v220
	v_permlane16_swap_b32_e32 v219, v221
	global_store_dwordx4 v230, v[218:221], s[52:53] offset:256
	s_cbranch_execz .LBB0_1253
